# v98 plus work-queue ticket atomic issued before the loop-top barrier (phases B and C)
# speedup vs baseline: 1.0066x; 1.0013x over previous
.LBB0_381:
	v_cmp_eq_u32_e32 vcc, 0, v1
	s_and_saveexec_b64 s[8:9], vcc
	s_cbranch_execz .Ldq_b
	s_mov_b64 s[12:13], exec
	v_mbcnt_lo_u32_b32 v1, s12, 0
	v_mbcnt_hi_u32_b32 v1, s13, v1
	v_cmp_eq_u32_e32 vcc, 0, v1
	s_and_saveexec_b64 s[10:11], vcc
	s_cbranch_execz .LBB0_384
	s_lshl_b64 s[14:15], s[58:59], 2
	s_add_u32 s14, s80, s14
	s_addc_u32 s15, s81, s15
	s_bcnt1_i32_b64 s12, s[12:13]
	v_mov_b32_e32 v2, s12
	global_atomic_add v2, v226, v2, s[14:15] sc0

.Ldq_b:
	s_barrier
	s_cbranch_execz .LBB0_385
	s_waitcnt vmcnt(0)
	v_readfirstlane_b32 s10, v2
	v_mov_b32_e32 v2, s4
	s_nop 0
	v_add_u32_e32 v1, s10, v1
	ds_write_b32 v2, v1

.LBB0_620:
	v_cmp_eq_u32_e32 vcc, 0, v234
	s_and_saveexec_b64 s[8:9], vcc
	s_cbranch_execz .Ldq_c
	s_mov_b64 s[12:13], exec
	v_mbcnt_lo_u32_b32 v1, s12, 0
	v_mbcnt_hi_u32_b32 v1, s13, v1
	v_cmp_eq_u32_e32 vcc, 0, v1
	s_and_saveexec_b64 s[10:11], vcc
	s_cbranch_execz .LBB0_623
	s_lshl_b64 s[14:15], s[58:59], 2
	s_add_u32 s14, s88, s14
	s_addc_u32 s15, s89, s15
	s_bcnt1_i32_b64 s12, s[12:13]
	v_mov_b32_e32 v2, s12
	global_atomic_add v2, v226, v2, s[14:15] offset:256 sc0
